# write-through (sc1) for the up-projection's h stores (streamed to the down-projection through the memory-side cache)
# speedup vs baseline: 1.0034x; 1.0034x over previous
; __device__ __forceinline__ u32x4 pack8(f32x4 a, f32x4 b) { u32x4 w; w.x = cvt_pk_bf16(a[0], a[1]); w.y = cvt_pk_bf16(a[2], a[3]); w.z = cvt_pk_bf16(b[0], b[1]); w.w = cvt_pk_bf16(b[2], b[3]); return w; }
;     __device__ __forceinline__ void operator()(const f32x4 (&acc)[2][2][4][2], const Unit& u, int wr, int wc, int fr, int fq) const {
;         const int colb = u.pn * 256 + wc * 32 + 8 * fq;
; #pragma unroll
;         for (int ai = 0; ai < 2; ++ai)
; #pragma unroll
;             for (int m = 0; m < 4; ++m) {
;                 const int row = u.pm * 256 + ai * 128 + wr * 64 + m * 16 + fr;
; #pragma unroll
;                 for (int bj = 0; bj < 2; ++bj) {
;                     f32x4 v0 = acc[ai][bj][m][0], v1 = acc[ai][bj][m][1];
; #pragma unroll
;                     for (int i = 0; i < 4; ++i) { const float a = fmaxf(v0[i], 0.f), b = fmaxf(v1[i], 0.f); v0[i] = a * a; v1[i] = b * b; }
;                     *(u32x4*)(H + (size_t)row * FF + colb + bj * 128) = pack8(v0, v1);
;                 }
;             }
;     }
.LBB0_1462:
	v_lshl_add_u32 v140, s56, 8, v142
	v_ashrrev_i32_e32 v141, 31, v140
	v_max_f32_e32 v124, 0, v124
	v_lshlrev_b64 v[148:149], 13, v[140:141]
	v_mul_f32_e32 v141, v124, v124
	v_lshl_or_b32 v146, s72, 8, v144
	v_max_f32_e32 v126, 0, v126
	v_max_f32_e32 v122, 0, v122
	v_max_f32_e32 v123, 0, v123
	v_max_f32_e32 v128, 0, v128
	v_max_f32_e32 v124, 0, v129
	v_ashrrev_i32_e32 v147, 31, v146
	v_mul_f32_e32 v126, v126, v126
	v_mul_f32_e32 v122, v122, v122
	v_max_f32_e32 v127, 0, v127
	v_mul_f32_e32 v123, v123, v123
	v_mul_f32_e32 v128, v128, v128
	v_max_f32_e32 v125, 0, v125
	v_mul_f32_e32 v129, v124, v124
	v_mul_f32_e32 v127, v127, v127
	v_mul_f32_e32 v150, v125, v125
	v_cvt_pk_bf16_f32 v124, v126, v127
	v_cvt_pk_bf16_f32 v125, v128, v129
	v_cvt_pk_bf16_f32 v126, v122, v123
	v_lshl_add_u64 v[128:129], s[18:19], 0, v[148:149]
	v_lshlrev_b64 v[122:123], 1, v[146:147]
	v_lshl_add_u64 v[128:129], v[128:129], 0, v[122:123]
	v_max_f32_e32 v114, 0, v114
	v_max_f32_e32 v115, 0, v115
	v_max_f32_e32 v116, 0, v116
	v_cvt_pk_bf16_f32 v127, v141, v150
	global_store_dwordx4 v[128:129], v[124:127], off sc1
	s_nop 1
	v_mul_f32_e32 v124, v114, v114
	v_max_f32_e32 v114, v119, v119
	v_mul_f32_e32 v119, v115, v115
	v_max_f32_e32 v115, v120, v120
	v_mul_f32_e32 v120, v116, v116
	v_max_f32_e32 v114, 0, v114
	v_max_f32_e32 v115, 0, v115
	v_max_f32_e32 v116, 0, v121
	v_max_f32_e32 v118, 0, v118
	v_mul_f32_e32 v114, v114, v114
	v_mul_f32_e32 v115, v115, v115
	v_max_f32_e32 v117, 0, v117
	v_mul_f32_e32 v116, v116, v116
	v_mul_f32_e32 v118, v118, v118
	v_mul_f32_e32 v117, v117, v117
	v_cvt_pk_bf16_f32 v114, v118, v114
	v_cvt_pk_bf16_f32 v115, v115, v116
	v_cvt_pk_bf16_f32 v116, v124, v119
	v_max_f32_e32 v106, 0, v106
	v_max_f32_e32 v107, 0, v107
	v_max_f32_e32 v108, 0, v108
	v_cvt_pk_bf16_f32 v117, v120, v117
	global_store_dwordx4 v[128:129], v[114:117], off offset:256 sc1
	s_nop 1
	v_max_f32_e32 v110, 0, v110
	v_or_b32_e32 v114, 16, v140
	v_mul_f32_e32 v116, v106, v106
	v_max_f32_e32 v106, v111, v111
	v_mul_f32_e32 v111, v107, v107
	v_max_f32_e32 v107, v112, v112
	v_mul_f32_e32 v112, v108, v108
	v_ashrrev_i32_e32 v115, 31, v114
	v_max_f32_e32 v106, 0, v106
	v_max_f32_e32 v107, 0, v107
	v_max_f32_e32 v108, 0, v113
	v_lshlrev_b64 v[114:115], 13, v[114:115]
	v_mul_f32_e32 v110, v110, v110
	v_mul_f32_e32 v106, v106, v106
	v_mul_f32_e32 v107, v107, v107
	v_mul_f32_e32 v108, v108, v108
	v_max_f32_e32 v109, 0, v109
	v_cvt_pk_bf16_f32 v106, v110, v106
	v_cvt_pk_bf16_f32 v107, v107, v108
	v_cvt_pk_bf16_f32 v108, v116, v111
	v_lshl_add_u64 v[110:111], s[18:19], 0, v[114:115]
	v_mul_f32_e32 v109, v109, v109
	v_lshl_add_u64 v[110:111], v[110:111], 0, v[122:123]
	v_max_f32_e32 v98, 0, v98
	v_max_f32_e32 v99, 0, v99
	v_max_f32_e32 v100, 0, v100
	v_cvt_pk_bf16_f32 v109, v112, v109
	global_store_dwordx4 v[110:111], v[106:109], off sc1
	s_nop 1
	v_mul_f32_e32 v106, v98, v98
	v_max_f32_e32 v98, v103, v103
	v_mul_f32_e32 v103, v99, v99
	v_max_f32_e32 v99, v104, v104
	v_mul_f32_e32 v104, v100, v100
	v_max_f32_e32 v98, 0, v98
	v_max_f32_e32 v99, 0, v99
	v_max_f32_e32 v100, 0, v105
	v_max_f32_e32 v102, 0, v102
	v_mul_f32_e32 v98, v98, v98
	v_mul_f32_e32 v99, v99, v99
	v_max_f32_e32 v101, 0, v101
	v_mul_f32_e32 v100, v100, v100
	v_mul_f32_e32 v102, v102, v102
	v_mul_f32_e32 v101, v101, v101
	v_cvt_pk_bf16_f32 v98, v102, v98
	v_cvt_pk_bf16_f32 v99, v99, v100
	v_cvt_pk_bf16_f32 v100, v106, v103
	v_max_f32_e32 v90, 0, v90
	v_max_f32_e32 v91, 0, v91
	v_max_f32_e32 v92, 0, v92
	v_cvt_pk_bf16_f32 v101, v104, v101
	global_store_dwordx4 v[110:111], v[98:101], off offset:256 sc1
	s_nop 1
	v_max_f32_e32 v94, 0, v94
	v_or_b32_e32 v98, 32, v140
	v_mul_f32_e32 v100, v90, v90
	v_max_f32_e32 v90, v95, v95
	v_mul_f32_e32 v95, v91, v91
	v_max_f32_e32 v91, v96, v96
	v_mul_f32_e32 v96, v92, v92
	v_ashrrev_i32_e32 v99, 31, v98
	v_max_f32_e32 v90, 0, v90
	v_max_f32_e32 v91, 0, v91
	v_max_f32_e32 v92, 0, v97
	v_lshlrev_b64 v[98:99], 13, v[98:99]
	v_mul_f32_e32 v94, v94, v94
	v_mul_f32_e32 v90, v90, v90
	v_mul_f32_e32 v91, v91, v91
	v_mul_f32_e32 v92, v92, v92
	v_max_f32_e32 v93, 0, v93
	v_cvt_pk_bf16_f32 v90, v94, v90
	v_cvt_pk_bf16_f32 v91, v91, v92
	v_cvt_pk_bf16_f32 v92, v100, v95
	v_lshl_add_u64 v[94:95], s[18:19], 0, v[98:99]
	v_mul_f32_e32 v93, v93, v93
	v_lshl_add_u64 v[94:95], v[94:95], 0, v[122:123]
	v_max_f32_e32 v82, 0, v82
	v_max_f32_e32 v83, 0, v83
	v_max_f32_e32 v84, 0, v84
	v_cvt_pk_bf16_f32 v93, v96, v93
	global_store_dwordx4 v[94:95], v[90:93], off sc1
	s_nop 1
	v_mul_f32_e32 v90, v82, v82
	v_max_f32_e32 v82, v87, v87
	v_mul_f32_e32 v87, v83, v83
	v_max_f32_e32 v83, v88, v88
	v_mul_f32_e32 v88, v84, v84
	v_max_f32_e32 v82, 0, v82
	v_max_f32_e32 v83, 0, v83
	v_max_f32_e32 v84, 0, v89
	v_max_f32_e32 v86, 0, v86
	v_mul_f32_e32 v82, v82, v82
	v_mul_f32_e32 v83, v83, v83
	v_max_f32_e32 v85, 0, v85
	v_mul_f32_e32 v84, v84, v84
	v_mul_f32_e32 v86, v86, v86
	v_mul_f32_e32 v85, v85, v85
	v_cvt_pk_bf16_f32 v82, v86, v82
	v_cvt_pk_bf16_f32 v83, v83, v84
	v_cvt_pk_bf16_f32 v84, v90, v87
	v_max_f32_e32 v74, 0, v74
	v_max_f32_e32 v75, 0, v75
	v_max_f32_e32 v76, 0, v76
	v_cvt_pk_bf16_f32 v85, v88, v85
	global_store_dwordx4 v[94:95], v[82:85], off offset:256 sc1
	s_nop 1
	v_max_f32_e32 v78, 0, v78
	v_or_b32_e32 v82, 48, v140
	v_mul_f32_e32 v84, v74, v74
	v_max_f32_e32 v74, v79, v79
	v_mul_f32_e32 v79, v75, v75
	v_max_f32_e32 v75, v80, v80
	v_mul_f32_e32 v80, v76, v76
	v_ashrrev_i32_e32 v83, 31, v82
	v_max_f32_e32 v74, 0, v74
	v_max_f32_e32 v75, 0, v75
	v_max_f32_e32 v76, 0, v81
	v_lshlrev_b64 v[82:83], 13, v[82:83]
	v_mul_f32_e32 v78, v78, v78
	v_mul_f32_e32 v74, v74, v74
	v_mul_f32_e32 v75, v75, v75
; __device__ __forceinline__ u32x4 pack8(f32x4 a, f32x4 b) { u32x4 w; w.x = cvt_pk_bf16(a[0], a[1]); w.y = cvt_pk_bf16(a[2], a[3]); w.z = cvt_pk_bf16(b[0], b[1]); w.w = cvt_pk_bf16(b[2], b[3]); return w; }
;     __device__ __forceinline__ void operator()(const f32x4 (&acc)[2][2][4][2], const Unit& u, int wr, int wc, int fr, int fq) const {
;         const int colb = u.pn * 256 + wc * 32 + 8 * fq;
; #pragma unroll
;         for (int ai = 0; ai < 2; ++ai)
; #pragma unroll
;             for (int m = 0; m < 4; ++m) {
;                 const int row = u.pm * 256 + ai * 128 + wr * 64 + m * 16 + fr;
; #pragma unroll
;                 for (int bj = 0; bj < 2; ++bj) {
;                     f32x4 v0 = acc[ai][bj][m][0], v1 = acc[ai][bj][m][1];
; #pragma unroll
;                     for (int i = 0; i < 4; ++i) { const float a = fmaxf(v0[i], 0.f), b = fmaxf(v1[i], 0.f); v0[i] = a * a; v1[i] = b * b; }
;                     *(u32x4*)(H + (size_t)row * FF + colb + bj * 128) = pack8(v0, v1);
;                 }
;             }
;     }
	v_mul_f32_e32 v76, v76, v76
	v_max_f32_e32 v77, 0, v77
	v_cvt_pk_bf16_f32 v74, v78, v74
	v_cvt_pk_bf16_f32 v75, v75, v76
	v_cvt_pk_bf16_f32 v76, v84, v79
	v_lshl_add_u64 v[78:79], s[18:19], 0, v[82:83]
	v_mul_f32_e32 v77, v77, v77
	v_lshl_add_u64 v[78:79], v[78:79], 0, v[122:123]
	v_max_f32_e32 v66, 0, v66
	v_max_f32_e32 v67, 0, v67
	v_max_f32_e32 v68, 0, v68
	v_cvt_pk_bf16_f32 v77, v80, v77
	global_store_dwordx4 v[78:79], v[74:77], off sc1
	s_nop 1
	v_mul_f32_e32 v74, v66, v66
	v_max_f32_e32 v66, v71, v71
	v_mul_f32_e32 v71, v67, v67
	v_max_f32_e32 v67, v72, v72
	v_mul_f32_e32 v72, v68, v68
	v_max_f32_e32 v66, 0, v66
	v_max_f32_e32 v67, 0, v67
	v_max_f32_e32 v68, 0, v73
	v_max_f32_e32 v70, 0, v70
	v_mul_f32_e32 v66, v66, v66
	v_mul_f32_e32 v67, v67, v67
	v_max_f32_e32 v69, 0, v69
	v_mul_f32_e32 v68, v68, v68
	v_mul_f32_e32 v70, v70, v70
	v_mul_f32_e32 v69, v69, v69
	v_cvt_pk_bf16_f32 v66, v70, v66
	v_cvt_pk_bf16_f32 v67, v67, v68
	v_cvt_pk_bf16_f32 v68, v74, v71
	v_max_f32_e32 v58, 0, v58
	v_max_f32_e32 v59, 0, v59
	v_max_f32_e32 v60, 0, v60
	v_cvt_pk_bf16_f32 v69, v72, v69
	global_store_dwordx4 v[78:79], v[66:69], off offset:256 sc1
	s_nop 1
	v_max_f32_e32 v62, 0, v62
	v_add_u32_e32 v66, 0x80, v140
	v_mul_f32_e32 v68, v58, v58
	v_max_f32_e32 v58, v63, v63
	v_mul_f32_e32 v63, v59, v59
	v_max_f32_e32 v59, v64, v64
	v_mul_f32_e32 v64, v60, v60
	v_ashrrev_i32_e32 v67, 31, v66
	v_max_f32_e32 v58, 0, v58
	v_max_f32_e32 v59, 0, v59
	v_max_f32_e32 v60, 0, v65
	v_lshlrev_b64 v[66:67], 13, v[66:67]
	v_mul_f32_e32 v62, v62, v62
	v_mul_f32_e32 v58, v58, v58
	v_mul_f32_e32 v59, v59, v59
	v_mul_f32_e32 v60, v60, v60
	v_max_f32_e32 v61, 0, v61
	v_cvt_pk_bf16_f32 v58, v62, v58
	v_cvt_pk_bf16_f32 v59, v59, v60
	v_cvt_pk_bf16_f32 v60, v68, v63
	v_lshl_add_u64 v[62:63], s[18:19], 0, v[66:67]
	v_mul_f32_e32 v61, v61, v61
	v_lshl_add_u64 v[62:63], v[62:63], 0, v[122:123]
	v_max_f32_e32 v50, 0, v50
	v_max_f32_e32 v51, 0, v51
	v_max_f32_e32 v52, 0, v52
	v_cvt_pk_bf16_f32 v61, v64, v61
	global_store_dwordx4 v[62:63], v[58:61], off sc1
	s_nop 1
	v_mul_f32_e32 v58, v50, v50
	v_max_f32_e32 v50, v55, v55
	v_mul_f32_e32 v55, v51, v51
	v_max_f32_e32 v51, v56, v56
	v_mul_f32_e32 v56, v52, v52
	v_max_f32_e32 v50, 0, v50
	v_max_f32_e32 v51, 0, v51
	v_max_f32_e32 v52, 0, v57
	v_max_f32_e32 v54, 0, v54
	v_mul_f32_e32 v50, v50, v50
	v_mul_f32_e32 v51, v51, v51
	v_max_f32_e32 v53, 0, v53
	v_mul_f32_e32 v52, v52, v52
	v_mul_f32_e32 v54, v54, v54
	v_mul_f32_e32 v53, v53, v53
	v_cvt_pk_bf16_f32 v50, v54, v50
	v_cvt_pk_bf16_f32 v51, v51, v52
	v_cvt_pk_bf16_f32 v52, v58, v55
	v_max_f32_e32 v42, 0, v42
	v_max_f32_e32 v43, 0, v43
	v_max_f32_e32 v44, 0, v44
	v_cvt_pk_bf16_f32 v53, v56, v53
	global_store_dwordx4 v[62:63], v[50:53], off offset:256 sc1
	s_nop 1
	v_max_f32_e32 v46, 0, v46
	v_add_u32_e32 v50, 0x90, v140
	v_mul_f32_e32 v52, v42, v42
	v_max_f32_e32 v42, v47, v47
	v_mul_f32_e32 v47, v43, v43
	v_max_f32_e32 v43, v48, v48
	v_mul_f32_e32 v48, v44, v44
	v_ashrrev_i32_e32 v51, 31, v50
	v_max_f32_e32 v42, 0, v42
	v_max_f32_e32 v43, 0, v43
	v_max_f32_e32 v44, 0, v49
	v_lshlrev_b64 v[50:51], 13, v[50:51]
	v_mul_f32_e32 v46, v46, v46
	v_mul_f32_e32 v42, v42, v42
	v_mul_f32_e32 v43, v43, v43
	v_mul_f32_e32 v44, v44, v44
	v_max_f32_e32 v45, 0, v45
	v_cvt_pk_bf16_f32 v42, v46, v42
	v_cvt_pk_bf16_f32 v43, v43, v44
	v_cvt_pk_bf16_f32 v44, v52, v47
	v_lshl_add_u64 v[46:47], s[18:19], 0, v[50:51]
	v_mul_f32_e32 v45, v45, v45
	v_lshl_add_u64 v[46:47], v[46:47], 0, v[122:123]
	v_max_f32_e32 v34, 0, v34
	v_max_f32_e32 v35, 0, v35
	v_max_f32_e32 v36, 0, v36
	v_cvt_pk_bf16_f32 v45, v48, v45
	global_store_dwordx4 v[46:47], v[42:45], off sc1
	s_nop 1
	v_mul_f32_e32 v42, v34, v34
	v_max_f32_e32 v34, v39, v39
	v_mul_f32_e32 v39, v35, v35
	v_max_f32_e32 v35, v40, v40
	v_mul_f32_e32 v40, v36, v36
; __device__ __forceinline__ u32x4 pack8(f32x4 a, f32x4 b) { u32x4 w; w.x = cvt_pk_bf16(a[0], a[1]); w.y = cvt_pk_bf16(a[2], a[3]); w.z = cvt_pk_bf16(b[0], b[1]); w.w = cvt_pk_bf16(b[2], b[3]); return w; }
;     __device__ __forceinline__ void operator()(const f32x4 (&acc)[2][2][4][2], const Unit& u, int wr, int wc, int fr, int fq) const {
;         const int colb = u.pn * 256 + wc * 32 + 8 * fq;
; #pragma unroll
;         for (int ai = 0; ai < 2; ++ai)
; #pragma unroll
;             for (int m = 0; m < 4; ++m) {
;                 const int row = u.pm * 256 + ai * 128 + wr * 64 + m * 16 + fr;
; #pragma unroll
;                 for (int bj = 0; bj < 2; ++bj) {
;                     f32x4 v0 = acc[ai][bj][m][0], v1 = acc[ai][bj][m][1];
; #pragma unroll
;                     for (int i = 0; i < 4; ++i) { const float a = fmaxf(v0[i], 0.f), b = fmaxf(v1[i], 0.f); v0[i] = a * a; v1[i] = b * b; }
;                     *(u32x4*)(H + (size_t)row * FF + colb + bj * 128) = pack8(v0, v1);
;                 }
;             }
;     }
	v_max_f32_e32 v34, 0, v34
	v_max_f32_e32 v35, 0, v35
	v_max_f32_e32 v36, 0, v41
	v_max_f32_e32 v38, 0, v38
	v_mul_f32_e32 v34, v34, v34
	v_mul_f32_e32 v35, v35, v35
	v_max_f32_e32 v37, 0, v37
	v_mul_f32_e32 v36, v36, v36
	v_mul_f32_e32 v38, v38, v38
	v_mul_f32_e32 v37, v37, v37
	v_cvt_pk_bf16_f32 v34, v38, v34
	v_cvt_pk_bf16_f32 v35, v35, v36
	v_cvt_pk_bf16_f32 v36, v42, v39
	v_max_f32_e32 v26, 0, v26
	v_max_f32_e32 v27, 0, v27
	v_max_f32_e32 v28, 0, v28
	v_cvt_pk_bf16_f32 v37, v40, v37
	global_store_dwordx4 v[46:47], v[34:37], off offset:256 sc1
	s_nop 1
	v_max_f32_e32 v30, 0, v30
	v_add_u32_e32 v34, 0xa0, v140
	v_mul_f32_e32 v36, v26, v26
	v_max_f32_e32 v26, v31, v31
	v_mul_f32_e32 v31, v27, v27
	v_max_f32_e32 v27, v32, v32
	v_mul_f32_e32 v32, v28, v28
	v_ashrrev_i32_e32 v35, 31, v34
	v_max_f32_e32 v26, 0, v26
	v_max_f32_e32 v27, 0, v27
	v_max_f32_e32 v28, 0, v33
	v_lshlrev_b64 v[34:35], 13, v[34:35]
	v_mul_f32_e32 v30, v30, v30
	v_mul_f32_e32 v26, v26, v26
	v_mul_f32_e32 v27, v27, v27
	v_mul_f32_e32 v28, v28, v28
	v_max_f32_e32 v29, 0, v29
	v_cvt_pk_bf16_f32 v26, v30, v26
	v_cvt_pk_bf16_f32 v27, v27, v28
	v_cvt_pk_bf16_f32 v28, v36, v31
	v_lshl_add_u64 v[30:31], s[18:19], 0, v[34:35]
	v_mul_f32_e32 v29, v29, v29
	v_lshl_add_u64 v[30:31], v[30:31], 0, v[122:123]
	v_max_f32_e32 v18, 0, v18
	v_max_f32_e32 v19, 0, v19
	v_max_f32_e32 v20, 0, v20
	v_cvt_pk_bf16_f32 v29, v32, v29
	global_store_dwordx4 v[30:31], v[26:29], off sc1
	s_nop 1
	v_mul_f32_e32 v26, v18, v18
	v_max_f32_e32 v18, v23, v23
	v_mul_f32_e32 v23, v19, v19
	v_max_f32_e32 v19, v24, v24
	v_mul_f32_e32 v24, v20, v20
	v_max_f32_e32 v18, 0, v18
	v_max_f32_e32 v19, 0, v19
	v_max_f32_e32 v20, 0, v25
	v_max_f32_e32 v22, 0, v22
	v_mul_f32_e32 v18, v18, v18
	v_mul_f32_e32 v19, v19, v19
	v_max_f32_e32 v21, 0, v21
	v_mul_f32_e32 v20, v20, v20
	v_mul_f32_e32 v22, v22, v22
	v_mul_f32_e32 v21, v21, v21
	v_cvt_pk_bf16_f32 v18, v22, v18
	v_cvt_pk_bf16_f32 v19, v19, v20
	v_cvt_pk_bf16_f32 v20, v26, v23
	v_max_f32_e32 v10, 0, v10
	v_max_f32_e32 v11, 0, v11
	v_max_f32_e32 v12, 0, v12
	v_cvt_pk_bf16_f32 v21, v24, v21
	global_store_dwordx4 v[30:31], v[18:21], off offset:256 sc1
	s_nop 1
	v_max_f32_e32 v14, 0, v14
	v_add_u32_e32 v18, 0xb0, v140
	v_mul_f32_e32 v20, v10, v10
	v_max_f32_e32 v10, v15, v15
	v_mul_f32_e32 v15, v11, v11
	v_max_f32_e32 v11, v16, v16
	v_mul_f32_e32 v16, v12, v12
	v_ashrrev_i32_e32 v19, 31, v18
	v_max_f32_e32 v10, 0, v10
	v_max_f32_e32 v11, 0, v11
	v_max_f32_e32 v12, 0, v17
	v_lshlrev_b64 v[18:19], 13, v[18:19]
	v_mul_f32_e32 v14, v14, v14
	v_mul_f32_e32 v10, v10, v10
	v_mul_f32_e32 v11, v11, v11
	v_mul_f32_e32 v12, v12, v12
	v_max_f32_e32 v13, 0, v13
	v_cvt_pk_bf16_f32 v10, v14, v10
	v_cvt_pk_bf16_f32 v11, v11, v12
	v_cvt_pk_bf16_f32 v12, v20, v15
	v_lshl_add_u64 v[14:15], s[18:19], 0, v[18:19]
	v_mul_f32_e32 v13, v13, v13
	v_lshl_add_u64 v[14:15], v[14:15], 0, v[122:123]
	v_max_f32_e32 v2, 0, v2
	v_max_f32_e32 v3, 0, v3
	v_max_f32_e32 v4, 0, v4
	v_cvt_pk_bf16_f32 v13, v16, v13
	global_store_dwordx4 v[14:15], v[10:13], off sc1
	s_nop 1
	v_mul_f32_e32 v10, v2, v2
	v_max_f32_e32 v2, v7, v7
	v_mul_f32_e32 v7, v3, v3
	v_max_f32_e32 v3, v8, v8
	v_mul_f32_e32 v8, v4, v4
	v_max_f32_e32 v2, 0, v2
	v_max_f32_e32 v3, 0, v3
	v_max_f32_e32 v4, 0, v9
	v_max_f32_e32 v5, 0, v5
	v_max_f32_e32 v6, 0, v6
	v_mul_f32_e32 v2, v2, v2
	v_mul_f32_e32 v3, v3, v3
	v_mul_f32_e32 v4, v4, v4
	v_mul_f32_e32 v5, v5, v5
	s_andn2_b64 vcc, exec, s[38:39]
	s_mov_b64 s[38:39], -1
	v_mul_f32_e32 v6, v6, v6
	v_cvt_pk_bf16_f32 v2, v6, v2
	v_cvt_pk_bf16_f32 v3, v3, v4
	v_cvt_pk_bf16_f32 v4, v10, v7
	v_cvt_pk_bf16_f32 v5, v8, v5
	global_store_dwordx4 v[14:15], v[2:5], off offset:256 sc1
	s_nop 1
	s_cbranch_vccnz .LBB0_1450
	s_andn2_b64 vcc, exec, s[0:1]
	s_cbranch_vccnz .LBB0_1449
	s_barrier
	s_branch .LBB0_1449
